# attnA: sub-LN gains staged in LDS during the unit prologue instead of 16 global loads in the epilogue
# baseline (speedup 1.0000x reference)
; #define LAS __attribute__((address_space(3)))
; __device__ __forceinline__ void subln_store(f32x16 (&o)[4], const float* subg, bf16_t* dst  , int lane) {
;     ...
;     f32x4 sg[4][4];
; #pragma unroll
;     for (int cb = 0; cb < 4; ++cb)
; #pragma unroll
;         for (int g = 0; g < 4; ++g) sg[cb][g] = *(const f32x4*)(subg + 32 * cb + 8 * g + 4 * hi);
; __device__ __forceinline__ void attnA_unit(const P2Ctx& C, int b, int h, int qb) {
;     LAS unsigned char* lds = C.lds; const int lane = C.lane, wid = C.wid, pf = C.pf;
;     const int comp = wid >> 2, qs = wid & 3, r32 = lane & 31, hi = lane >> 5;
;     const int q0 = qb * 128, trow0 = b * SEQ;
;     const int qpos = q0 + qs * 32 + r32; const size_t qrow = (size_t)(trow0 + qpos);
;     const int qcw = (q0 + qs * 32) >> 6, ntw = qcw + 1, NT = 2 * qb + 2;
;     const LAS float* lut = (const LAS float*)(lds + LUT_OFF) + h * 256;
;     const float lam = *(const LAS float*)(lds + LAM_OFF);
;     bf16x8 qf[4];
; #pragma unroll
;     for (int ds = 0; ds < 4; ++ds) qf[ds] = *(const bf16x8*)(C.Q + qrow * DM + h * 128 + comp * 64 + ds * 16 + hi * 8);
;     const int kkey = 8 * wid + (lane >> 3), kchs = (lane & 7) ^ ((kkey >> 1) & 7);
;     const bf16_t* ksrc = C.Kb + ((size_t)trow0 + kkey) * DM + h * 128 + kchs * 8;
;     const bf16_t* vsrc[2];
; #pragma unroll
;     for (int i = 0; i < 2; ++i) { const int p = 2 * wid + i, kg = p >> 1, cbv = 2 * (p & 1) + (lane >> 5), vkey = kg * 8 + ((lane >> 2) & 7), vch = cbv * 4 + (lane & 3);
;         vsrc[i] = C.Vb + ((size_t)trow0 + vkey) * DM + h * 128 + vch * 8; }
.LBB0_572:
	s_andn2_b64 vcc, exec, s[6:7]
	s_cbranch_vccnz .LBB0_614
	s_sub_i32 s6, s37, 32
	s_and_b32 s11, s6, 7
	s_lshr_b32 s6, s6, 3
	s_sub_i32 s10, 15, s6
	s_lshr_b32 s8, s83, 2
	s_and_b32 s9, s83, 3
	s_lshl_b32 s12, s10, 1
	s_add_i32 s12, s12, 2
	s_lshr_b32 s6, s9, 1
	s_lshl_b32 s13, s10, 1
	s_add_i32 s13, s13, s6
	s_add_i32 s13, s13, 1
	s_lshl_b32 s22, s83, 10
	s_lshl_b32 s23, s83, 11
	s_add_i32 s23, s23, 0x4000
	s_lshl_b32 s6, s10, 7
	s_lshl_b32 s7, s9, 5
	s_add_i32 s15, s6, s7
	s_add_i32 s26, s15, 0xffffff01
	s_mov_b32 s25, 0
	v_and_b32_e32 v100, 31, v219
	v_lshrrev_b32_e32 v101, 5, v219
	s_load_dwordx2 s[20:21], s[62:63], 0x80
	v_lshlrev_b32_e32 v107, 4, v196
	s_waitcnt lgkmcnt(0)
	v_cmp_gt_u32_e32 vcc, 32, v196
	s_and_saveexec_b64 s[6:7], vcc
	global_load_dwordx4 v[108:111], v107, s[20:21]
	s_or_b64 exec, exec, s[6:7]
	s_lshl_b32 s6, s11, 11
	s_add_i32 s6, s6, s15
	s_lshl_b32 s6, s6, 11
	s_lshl_b32 s7, s81, 1
	s_add_i32 s6, s6, s7
	s_lshl_b32 s7, s8, 7
	s_add_i32 s6, s6, s7
	s_add_u32 s20, s76, s6
	s_addc_u32 s21, s77, 0
	v_lshlrev_b32_e32 v102, 11, v100
	v_lshl_add_u32 v102, v101, 4, v102
	global_load_dwordx4 v[164:167], v102, s[20:21]
	global_load_dwordx4 v[168:171], v102, s[20:21] offset:32
	global_load_dwordx4 v[172:175], v102, s[20:21] offset:64
	global_load_dwordx4 v[176:179], v102, s[20:21] offset:96
	s_lshl_b32 s6, s11, 22
	s_lshl_b32 s7, s81, 1
	s_add_i32 s6, s6, s7
	s_add_u32 s16, s72, s6
	s_addc_u32 s17, s73, 0
	s_add_u32 s18, s74, s6
	s_addc_u32 s19, s75, 0
	s_mov_b32 s24, 0
	v_lshrrev_b32_e32 v103, 3, v219
	s_lshl_b32 s6, s83, 3
	v_add_u32_e32 v103, s6, v103
	v_bfe_u32 v104, v103, 1, 3
	v_and_b32_e32 v105, 7, v219
	v_xor_b32_e32 v104, v104, v105
	v_lshlrev_b32_e32 v104, 4, v104
	v_lshl_add_u32 v197, v103, 11, v104
	v_bfe_u32 v103, v219, 2, 3
	v_add_u32_e32 v103, s6, v103
	v_and_b32_e32 v104, 3, v219
	v_lshlrev_b32_e32 v104, 4, v104
	v_lshl_add_u32 v104, v101, 6, v104
	v_lshl_add_u32 v198, v103, 11, v104
	s_and_b32 s6, s24, 3
	s_lshl_b32 s6, s6, 15
	s_add_i32 s7, s6, s22
	s_mov_b32 m0, s7
	s_add_u32 s20, s16, 0x80
	s_addc_u32 s21, s17, 0
	s_add_i32 s29, s6, s23
	global_load_lds_dwordx4 v197, s[16:17]
	s_add_i32 m0, s7, 0x2000
	s_add_u32 s16, s16, 0x20000
	s_addc_u32 s17, s17, 0
	s_nop 0
	global_load_lds_dwordx4 v197, s[20:21]
	s_mov_b32 m0, s29
	s_add_u32 s20, s18, 0x80
	s_addc_u32 s21, s19, 0
	s_nop 0
	global_load_lds_dwordx4 v198, s[18:19]
	s_add_i32 m0, s29, 0x400
	s_add_u32 s18, s18, 0x20000
	s_addc_u32 s19, s19, 0
	s_add_i32 s24, s24, 1
	global_load_lds_dwordx4 v198, s[20:21]
	s_and_b32 s6, s24, 3
	s_lshl_b32 s6, s6, 15
	s_add_i32 s7, s6, s22
	s_mov_b32 m0, s7
	s_add_u32 s20, s16, 0x80
	s_addc_u32 s21, s17, 0
	s_add_i32 s29, s6, s23
	global_load_lds_dwordx4 v197, s[16:17]
	s_add_i32 m0, s7, 0x2000
	s_add_u32 s16, s16, 0x20000
	s_addc_u32 s17, s17, 0
	s_nop 0
	global_load_lds_dwordx4 v197, s[20:21]
	s_mov_b32 m0, s29
	s_add_u32 s20, s18, 0x80
	s_addc_u32 s21, s19, 0
	s_nop 0
	global_load_lds_dwordx4 v198, s[18:19]
	s_add_i32 m0, s29, 0x400
	s_add_u32 s18, s18, 0x20000
	s_addc_u32 s19, s19, 0
	s_add_i32 s24, s24, 1
	global_load_lds_dwordx4 v198, s[20:21]
	v_bfe_u32 v103, v100, 1, 3
	v_lshlrev_b32_e32 v104, 7, v100
	s_lshl_b32 s6, s8, 13
	v_add_u32_e32 v104, s6, v104
	v_or_b32_e32 v105, 0, v101
	v_xor_b32_e32 v105, v105, v103
	v_lshl_add_u32 v200, v105, 4, v104
	v_or_b32_e32 v105, 2, v101
	v_xor_b32_e32 v105, v105, v103
	v_lshl_add_u32 v201, v105, 4, v104
	v_or_b32_e32 v105, 4, v101
	v_xor_b32_e32 v105, v105, v103
	v_lshl_add_u32 v202, v105, 4, v104
	v_or_b32_e32 v105, 6, v101
	v_xor_b32_e32 v105, v105, v103
	v_lshl_add_u32 v203, v105, 4, v104
	v_bfe_u32 v103, v219, 2, 2
	v_lshl_add_u32 v103, v101, 2, v103
	v_lshlrev_b32_e32 v103, 6, v103
	v_bfe_u32 v104, v219, 4, 1
	v_lshl_add_u32 v103, v104, 5, v103
	v_and_b32_e32 v104, 3, v219
	v_lshl_add_u32 v103, v104, 3, v103
	v_add_u32_e32 v204, 0x4000, v103
	s_sub_i32 s6, 0x120, s15
	s_lshl_b32 s6, s6, 2
	s_add_i32 s6, s6, 0x22400
	v_lshlrev_b32_e32 v103, 4, v101
	v_lshlrev_b32_e32 v104, 2, v100
	v_sub_u32_e32 v103, v103, v104
	v_add_u32_e32 v236, s6, v103
	v_cmp_gt_u32_e32 vcc, 0x160, v196
	s_and_saveexec_b64 s[6:7], vcc
	s_cbranch_execz .LaA_padskip_1
	v_subrev_u32_e32 v103, 0x60, v196
	v_max_i32_e32 v104, 0, v103
	v_lshl_add_u32 v104, v104, 2, s42
	ds_read_b32 v105, v104
	v_cmp_gt_i32_e32 vcc, 0, v103
	v_mov_b32_e32 v106, 0x22400
	v_lshl_add_u32 v104, v196, 2, v106
	s_waitcnt lgkmcnt(0)
	v_cndmask_b32_e64 v105, v105, 0, vcc
	ds_write_b32 v104, v105
; #define A_WAITBAR(ahead) do { if ((ahead) >= 2) asm volatile("s_waitcnt vmcnt(8)" ::: "memory"); else if ((ahead) == 1) asm volatile("s_waitcnt vmcnt(4)" ::: "memory"); else asm volatile("s_waitcnt vmcnt(0)" ::: "memory"); \
;         __builtin_amdgcn_s_barrier(); asm volatile("" ::: "memory"); } while (0)
; __device__ __forceinline__ void attnA_unit(const P2Ctx& C, int b, int h, int qb) {
;     ...
;     f32x16 o[4];
; #pragma unroll
;     for (int cb = 0; cb < 4; ++cb)
; #pragma unroll
;         for (int r = 0; r < 16; ++r) o[cb][r] = 0.f;
;     float mhat = 0.f, l = 0.f;
;     bf16x8 pf_[4];
; #pragma unroll
;     for (int i = 0; i < 4; ++i) pf_[i] = (bf16x8){0, 0, 0, 0, 0, 0, 0, 0};
;     ...
;     A_DMA(0); A_DMA(1);
;     A_WAITBAR(1);
;     { if (2 < NT && !(pf & 16)) A_DMA(2);
.LaA_padskip_1:
	s_or_b64 exec, exec, s[6:7]
	v_mov_b32_e32 v4, 0
	v_mov_b32_e32 v5, 0
	v_mov_b32_e32 v6, 0
	v_mov_b32_e32 v7, 0
	v_mov_b32_e32 v8, 0
	v_mov_b32_e32 v9, 0
	v_mov_b32_e32 v10, 0
	v_mov_b32_e32 v11, 0
	v_mov_b32_e32 v12, 0
	v_mov_b32_e32 v13, 0
	v_mov_b32_e32 v14, 0
	v_mov_b32_e32 v15, 0
	v_mov_b32_e32 v16, 0
	v_mov_b32_e32 v17, 0
	v_mov_b32_e32 v18, 0
	v_mov_b32_e32 v19, 0
	v_mov_b32_e32 v20, 0
	v_mov_b32_e32 v21, 0
	v_mov_b32_e32 v22, 0
	v_mov_b32_e32 v23, 0
	v_mov_b32_e32 v24, 0
	v_mov_b32_e32 v25, 0
	v_mov_b32_e32 v26, 0
	v_mov_b32_e32 v27, 0
	v_mov_b32_e32 v28, 0
	v_mov_b32_e32 v29, 0
	v_mov_b32_e32 v30, 0
	v_mov_b32_e32 v31, 0
	v_mov_b32_e32 v32, 0
	v_mov_b32_e32 v33, 0
	v_mov_b32_e32 v34, 0
	v_mov_b32_e32 v35, 0
	v_mov_b32_e32 v36, 0
	v_mov_b32_e32 v37, 0
	v_mov_b32_e32 v38, 0
	v_mov_b32_e32 v39, 0
	v_mov_b32_e32 v40, 0
	v_mov_b32_e32 v41, 0
	v_mov_b32_e32 v42, 0
	v_mov_b32_e32 v43, 0
	v_mov_b32_e32 v44, 0
	v_mov_b32_e32 v45, 0
	v_mov_b32_e32 v46, 0
	v_mov_b32_e32 v47, 0
	v_mov_b32_e32 v48, 0
	v_mov_b32_e32 v49, 0
	v_mov_b32_e32 v50, 0
	v_mov_b32_e32 v51, 0
	v_mov_b32_e32 v52, 0
	v_mov_b32_e32 v53, 0
	v_mov_b32_e32 v54, 0
	v_mov_b32_e32 v55, 0
	v_mov_b32_e32 v56, 0
	v_mov_b32_e32 v57, 0
	v_mov_b32_e32 v58, 0
	v_mov_b32_e32 v59, 0
	v_mov_b32_e32 v60, 0
	v_mov_b32_e32 v61, 0
	v_mov_b32_e32 v62, 0
	v_mov_b32_e32 v63, 0
	v_mov_b32_e32 v64, 0
	v_mov_b32_e32 v65, 0
	v_mov_b32_e32 v66, 0
	v_mov_b32_e32 v67, 0
	v_mov_b32_e32 v220, 0
	v_mov_b32_e32 v221, 0
	v_mov_b32_e32 v222, 0
	v_mov_b32_e32 v223, 0
	v_mov_b32_e32 v224, 0
	v_mov_b32_e32 v225, 0
	v_mov_b32_e32 v226, 0
	v_mov_b32_e32 v227, 0
	v_mov_b32_e32 v228, 0
	v_mov_b32_e32 v229, 0
	v_mov_b32_e32 v230, 0
	v_mov_b32_e32 v231, 0
	v_mov_b32_e32 v232, 0
	v_mov_b32_e32 v233, 0
	v_mov_b32_e32 v234, 0
	v_mov_b32_e32 v235, 0
	v_mov_b32_e32 v240, 0
	v_mov_b32_e32 v241, 0
	s_mov_b32 s14, 0
	s_waitcnt vmcnt(4) lgkmcnt(0)
	v_cmp_gt_u32_e32 vcc, 32, v196
	v_add_u32_e32 v107, 0x22a00, v107
	s_and_saveexec_b64 s[6:7], vcc
	ds_write_b128 v107, v[108:111]
	s_or_b64 exec, exec, s[6:7]
	s_waitcnt lgkmcnt(0)
	s_barrier
	s_cmp_lt_u32 s24, s12
	s_cbranch_scc0 .LaA_nodma_2
	s_and_b32 s6, s24, 3
	s_lshl_b32 s6, s6, 15
	s_add_i32 s7, s6, s22
	s_mov_b32 m0, s7
	s_add_u32 s20, s16, 0x80
	s_addc_u32 s21, s17, 0
	s_add_i32 s29, s6, s23
	global_load_lds_dwordx4 v197, s[16:17]
	s_add_i32 m0, s7, 0x2000
	s_add_u32 s16, s16, 0x20000
	s_addc_u32 s17, s17, 0
	s_nop 0
	global_load_lds_dwordx4 v197, s[20:21]
	s_mov_b32 m0, s29
	s_add_u32 s20, s18, 0x80
	s_addc_u32 s21, s19, 0
	s_nop 0
	global_load_lds_dwordx4 v198, s[18:19]
	s_add_i32 m0, s29, 0x400
	s_add_u32 s18, s18, 0x20000
	s_addc_u32 s19, s19, 0
	s_add_i32 s24, s24, 1
	global_load_lds_dwordx4 v198, s[20:21]

; #define LAS __attribute__((address_space(3)))
; __device__ __forceinline__ void subln_store(f32x16 (&o)[4], const float* subg, bf16_t* dst  , int lane) {
;     ...
;     f32x4 sg[4][4];
; #pragma unroll
;     for (int cb = 0; cb < 4; ++cb)
; #pragma unroll
;         for (int g = 0; g < 4; ++g) sg[cb][g] = *(const f32x4*)(subg + 32 * cb + 8 * g + 4 * hi);
; __device__ __forceinline__ void attnA_unit(const P2Ctx& C, int b, int h, int qb) {
;     ...
;     l += __shfl_xor(l, 32);
;     const float inv = 1.0f / l;
;     LAS float* X2 = (LAS float*)(lds + 65536);
;     if (comp == 1) {
; #pragma unroll
;         for (int cb = 0; cb < 4; ++cb)
; #pragma unroll
;             for (int r = 0; r < 16; ++r) X2[((qs * 4 + cb) * 16 + r) * 64 + lane] = o[cb][r] * inv;
;     }
;     __syncthreads();
;     if (comp == 0) {
; #pragma unroll
;         for (int cb = 0; cb < 4; ++cb)
; #pragma unroll
;             for (int r = 0; r < 16; ++r) o[cb][r] = o[cb][r] * inv - lam * X2[((qs * 4 + cb) * 16 + r) * 64 + lane];
;         subln_store(o, C.a->in[I_SUBG], C.AO + qrow * DM + h * 128, lane);
.LaA_comp0_14:
	v_lshrrev_b32_e32 v242, 5, v219
	v_lshlrev_b32_e32 v242, 4, v242
	v_add_u32_e32 v242, 0x22a00, v242
	ds_read_b128 v[100:103], v242 offset:0
	ds_read_b128 v[104:107], v242 offset:32
	ds_read_b128 v[108:111], v242 offset:64
	ds_read_b128 v[112:115], v242 offset:96
	ds_read_b128 v[116:119], v242 offset:128
	ds_read_b128 v[120:123], v242 offset:160
	ds_read_b128 v[124:127], v242 offset:192
	ds_read_b128 v[128:131], v242 offset:224
	s_waitcnt lgkmcnt(4)
	ds_read_b128 v[132:135], v242 offset:256
	ds_read_b128 v[136:139], v242 offset:288
	ds_read_b128 v[140:143], v242 offset:320
	ds_read_b128 v[144:147], v242 offset:352
	ds_read_b128 v[148:151], v242 offset:384
	ds_read_b128 v[152:155], v242 offset:416
	ds_read_b128 v[156:159], v242 offset:448
	ds_read_b128 v[160:163], v242 offset:480
	s_waitcnt lgkmcnt(6)
	ds_read_b32 v243, v207
	s_nop 7
	s_nop 3
	v_mul_f32_e32 v4, v4, v241
	v_mul_f32_e32 v5, v5, v241
	v_mul_f32_e32 v6, v6, v241
	v_mul_f32_e32 v7, v7, v241
	v_mul_f32_e32 v8, v8, v241
	v_mul_f32_e32 v9, v9, v241
	v_mul_f32_e32 v10, v10, v241
	v_mul_f32_e32 v11, v11, v241
	v_mul_f32_e32 v12, v12, v241
	v_mul_f32_e32 v13, v13, v241
	v_mul_f32_e32 v14, v14, v241
	v_mul_f32_e32 v15, v15, v241
	v_mul_f32_e32 v16, v16, v241
	v_mul_f32_e32 v17, v17, v241
	v_mul_f32_e32 v18, v18, v241
	v_mul_f32_e32 v19, v19, v241
	v_mul_f32_e32 v20, v20, v241
	v_mul_f32_e32 v21, v21, v241
	v_mul_f32_e32 v22, v22, v241
	v_mul_f32_e32 v23, v23, v241
	v_mul_f32_e32 v24, v24, v241
	v_mul_f32_e32 v25, v25, v241
	v_mul_f32_e32 v26, v26, v241
	v_mul_f32_e32 v27, v27, v241
	v_mul_f32_e32 v28, v28, v241
	v_mul_f32_e32 v29, v29, v241
	v_mul_f32_e32 v30, v30, v241
	v_mul_f32_e32 v31, v31, v241
	v_mul_f32_e32 v32, v32, v241
	v_mul_f32_e32 v33, v33, v241
	v_mul_f32_e32 v34, v34, v241
	v_mul_f32_e32 v35, v35, v241
	v_mul_f32_e32 v36, v36, v241
	v_mul_f32_e32 v37, v37, v241
	v_mul_f32_e32 v38, v38, v241
	v_mul_f32_e32 v39, v39, v241
	v_mul_f32_e32 v40, v40, v241
	v_mul_f32_e32 v41, v41, v241
	v_mul_f32_e32 v42, v42, v241
	v_mul_f32_e32 v43, v43, v241
	v_mul_f32_e32 v44, v44, v241
	v_mul_f32_e32 v45, v45, v241
	v_mul_f32_e32 v46, v46, v241
	v_mul_f32_e32 v47, v47, v241
	v_mul_f32_e32 v48, v48, v241
	v_mul_f32_e32 v49, v49, v241
	v_mul_f32_e32 v50, v50, v241
	v_mul_f32_e32 v51, v51, v241
	v_mul_f32_e32 v52, v52, v241
	v_mul_f32_e32 v53, v53, v241
	v_mul_f32_e32 v54, v54, v241
	v_mul_f32_e32 v55, v55, v241
	v_mul_f32_e32 v56, v56, v241
	v_mul_f32_e32 v57, v57, v241
	v_mul_f32_e32 v58, v58, v241
	v_mul_f32_e32 v59, v59, v241
	v_mul_f32_e32 v60, v60, v241
	v_mul_f32_e32 v61, v61, v241
	v_mul_f32_e32 v62, v62, v241
	v_mul_f32_e32 v63, v63, v241
	v_mul_f32_e32 v64, v64, v241
	v_mul_f32_e32 v65, v65, v241
	v_mul_f32_e32 v66, v66, v241
	v_mul_f32_e32 v67, v67, v241
	s_waitcnt lgkmcnt(0)
	s_barrier
	ds_read2st64_b32 v[164:165], v2 offset0:0 offset1:1
	ds_read2st64_b32 v[166:167], v2 offset0:2 offset1:3
	ds_read2st64_b32 v[168:169], v2 offset0:4 offset1:5
	ds_read2st64_b32 v[170:171], v2 offset0:6 offset1:7
	ds_read2st64_b32 v[172:173], v2 offset0:8 offset1:9
	ds_read2st64_b32 v[174:175], v2 offset0:10 offset1:11
	ds_read2st64_b32 v[176:177], v2 offset0:12 offset1:13
	ds_read2st64_b32 v[178:179], v2 offset0:14 offset1:15
	ds_read2st64_b32 v[180:181], v2 offset0:16 offset1:17
	ds_read2st64_b32 v[182:183], v2 offset0:18 offset1:19
	ds_read2st64_b32 v[184:185], v2 offset0:20 offset1:21
	ds_read2st64_b32 v[186:187], v2 offset0:22 offset1:23
	ds_read2st64_b32 v[188:189], v2 offset0:24 offset1:25
	ds_read2st64_b32 v[190:191], v2 offset0:26 offset1:27
	ds_read2st64_b32 v[192:193], v2 offset0:28 offset1:29
	s_waitcnt lgkmcnt(8)
	ds_read2st64_b32 v[194:195], v2 offset0:30 offset1:31
	ds_read2st64_b32 v[68:69], v2 offset0:32 offset1:33
	ds_read2st64_b32 v[70:71], v2 offset0:34 offset1:35
	ds_read2st64_b32 v[72:73], v2 offset0:36 offset1:37
	ds_read2st64_b32 v[74:75], v2 offset0:38 offset1:39
	ds_read2st64_b32 v[76:77], v2 offset0:40 offset1:41
	ds_read2st64_b32 v[78:79], v2 offset0:42 offset1:43
	ds_read2st64_b32 v[80:81], v2 offset0:44 offset1:45
	ds_read2st64_b32 v[82:83], v2 offset0:46 offset1:47
	ds_read2st64_b32 v[84:85], v2 offset0:48 offset1:49
	ds_read2st64_b32 v[86:87], v2 offset0:50 offset1:51
	ds_read2st64_b32 v[88:89], v2 offset0:52 offset1:53
	ds_read2st64_b32 v[90:91], v2 offset0:54 offset1:55
	ds_read2st64_b32 v[92:93], v2 offset0:56 offset1:57
	ds_read2st64_b32 v[94:95], v2 offset0:58 offset1:59
	ds_read2st64_b32 v[96:97], v2 offset0:60 offset1:61
	ds_read2st64_b32 v[98:99], v2 offset0:62 offset1:63
	s_waitcnt lgkmcnt(0)
; __device__ __forceinline__ void subln_store(f32x16 (&o)[4], const float* subg, bf16_t* dst  , int lane) {
;     const int hi = lane >> 5;
;     float ss = 0.f;
; #pragma unroll
;     for (int cb = 0; cb < 4; ++cb)
; #pragma unroll
;         for (int r = 0; r < 16; ++r) ss += o[cb][r] * o[cb][r];
;     ss += __shfl_xor(ss, 32);
;     const float rstd = (1.0f - LAMBDA_INIT) / sqrtf(ss * (1.0f / 128.0f) + EPS);
; __device__ __forceinline__ void attnA_unit(const P2Ctx& C, int b, int h, int qb) {
;     ...
;     if (comp == 0) {
; #pragma unroll
;         for (int cb = 0; cb < 4; ++cb)
; #pragma unroll
;             for (int r = 0; r < 16; ++r) o[cb][r] = o[cb][r] * inv - lam * X2[((qs * 4 + cb) * 16 + r) * 64 + lane];
	v_fma_f32 v4, -v243, v164, v4
	v_fma_f32 v5, -v243, v165, v5
	v_fma_f32 v6, -v243, v166, v6
	v_fma_f32 v7, -v243, v167, v7
	v_fma_f32 v8, -v243, v168, v8
	v_fma_f32 v9, -v243, v169, v9
	v_fma_f32 v10, -v243, v170, v10
	v_fma_f32 v11, -v243, v171, v11
	v_fma_f32 v12, -v243, v172, v12
	v_fma_f32 v13, -v243, v173, v13
	v_fma_f32 v14, -v243, v174, v14
	v_fma_f32 v15, -v243, v175, v15
	v_fma_f32 v16, -v243, v176, v16
	v_fma_f32 v17, -v243, v177, v17
	v_fma_f32 v18, -v243, v178, v18
	v_fma_f32 v19, -v243, v179, v19
	v_fma_f32 v20, -v243, v180, v20
	v_fma_f32 v21, -v243, v181, v21
	v_fma_f32 v22, -v243, v182, v22
	v_fma_f32 v23, -v243, v183, v23
	v_fma_f32 v24, -v243, v184, v24
	v_fma_f32 v25, -v243, v185, v25
	v_fma_f32 v26, -v243, v186, v26
	v_fma_f32 v27, -v243, v187, v27
	v_fma_f32 v28, -v243, v188, v28
	v_fma_f32 v29, -v243, v189, v29
	v_fma_f32 v30, -v243, v190, v30
	v_fma_f32 v31, -v243, v191, v31
	v_fma_f32 v32, -v243, v192, v32
	v_fma_f32 v33, -v243, v193, v33
	v_fma_f32 v34, -v243, v194, v34
	v_fma_f32 v35, -v243, v195, v35
	v_fma_f32 v36, -v243, v68, v36
	v_fma_f32 v37, -v243, v69, v37
	v_fma_f32 v38, -v243, v70, v38
	v_fma_f32 v39, -v243, v71, v39
	v_fma_f32 v40, -v243, v72, v40
	v_fma_f32 v41, -v243, v73, v41
	v_fma_f32 v42, -v243, v74, v42
	v_fma_f32 v43, -v243, v75, v43
	v_fma_f32 v44, -v243, v76, v44
	v_fma_f32 v45, -v243, v77, v45
	v_fma_f32 v46, -v243, v78, v46
	v_fma_f32 v47, -v243, v79, v47
	v_fma_f32 v48, -v243, v80, v48
	v_fma_f32 v49, -v243, v81, v49
	v_fma_f32 v50, -v243, v82, v50
	v_fma_f32 v51, -v243, v83, v51
	v_fma_f32 v52, -v243, v84, v52
	v_fma_f32 v53, -v243, v85, v53
	v_fma_f32 v54, -v243, v86, v54
	v_fma_f32 v55, -v243, v87, v55
	v_fma_f32 v56, -v243, v88, v56
	v_fma_f32 v57, -v243, v89, v57
	v_fma_f32 v58, -v243, v90, v58
	v_fma_f32 v59, -v243, v91, v59
	v_fma_f32 v60, -v243, v92, v60
	v_fma_f32 v61, -v243, v93, v61
	v_fma_f32 v62, -v243, v94, v62
	v_fma_f32 v63, -v243, v95, v63
	v_fma_f32 v64, -v243, v96, v64
	v_fma_f32 v65, -v243, v97, v65
	v_fma_f32 v66, -v243, v98, v66
	v_fma_f32 v67, -v243, v99, v67
	v_mul_f32_e32 v245, v4, v4
	v_fmac_f32_e32 v245, v5, v5
	v_fmac_f32_e32 v245, v6, v6
	v_fmac_f32_e32 v245, v7, v7
	v_fmac_f32_e32 v245, v8, v8
	v_fmac_f32_e32 v245, v9, v9
	v_fmac_f32_e32 v245, v10, v10
	v_fmac_f32_e32 v245, v11, v11
	v_fmac_f32_e32 v245, v12, v12
	v_fmac_f32_e32 v245, v13, v13
	v_fmac_f32_e32 v245, v14, v14
	v_fmac_f32_e32 v245, v15, v15
	v_fmac_f32_e32 v245, v16, v16
	v_fmac_f32_e32 v245, v17, v17
	v_fmac_f32_e32 v245, v18, v18
	v_fmac_f32_e32 v245, v19, v19
	v_fmac_f32_e32 v245, v20, v20
	v_fmac_f32_e32 v245, v21, v21
	v_fmac_f32_e32 v245, v22, v22
	v_fmac_f32_e32 v245, v23, v23
	v_fmac_f32_e32 v245, v24, v24
	v_fmac_f32_e32 v245, v25, v25
	v_fmac_f32_e32 v245, v26, v26
	v_fmac_f32_e32 v245, v27, v27
	v_fmac_f32_e32 v245, v28, v28
	v_fmac_f32_e32 v245, v29, v29
	v_fmac_f32_e32 v245, v30, v30
	v_fmac_f32_e32 v245, v31, v31
	v_fmac_f32_e32 v245, v32, v32
	v_fmac_f32_e32 v245, v33, v33
	v_fmac_f32_e32 v245, v34, v34
	v_fmac_f32_e32 v245, v35, v35
	v_fmac_f32_e32 v245, v36, v36
	v_fmac_f32_e32 v245, v37, v37
	v_fmac_f32_e32 v245, v38, v38
	v_fmac_f32_e32 v245, v39, v39
	v_fmac_f32_e32 v245, v40, v40
	v_fmac_f32_e32 v245, v41, v41
	v_fmac_f32_e32 v245, v42, v42
	v_fmac_f32_e32 v245, v43, v43
	v_fmac_f32_e32 v245, v44, v44
	v_fmac_f32_e32 v245, v45, v45
	v_fmac_f32_e32 v245, v46, v46
	v_fmac_f32_e32 v245, v47, v47
	v_fmac_f32_e32 v245, v48, v48
	v_fmac_f32_e32 v245, v49, v49
	v_fmac_f32_e32 v245, v50, v50
	v_fmac_f32_e32 v245, v51, v51
	v_fmac_f32_e32 v245, v52, v52
	v_fmac_f32_e32 v245, v53, v53
	v_fmac_f32_e32 v245, v54, v54
	v_fmac_f32_e32 v245, v55, v55
	v_fmac_f32_e32 v245, v56, v56
	v_fmac_f32_e32 v245, v57, v57
	v_fmac_f32_e32 v245, v58, v58
	v_fmac_f32_e32 v245, v59, v59
	v_fmac_f32_e32 v245, v60, v60
	v_fmac_f32_e32 v245, v61, v61
	v_fmac_f32_e32 v245, v62, v62
	v_fmac_f32_e32 v245, v63, v63
	v_fmac_f32_e32 v245, v64, v64
	v_fmac_f32_e32 v245, v65, v65
	v_fmac_f32_e32 v245, v66, v66
	v_fmac_f32_e32 v245, v67, v67
	v_mov_b32_e32 v246, v245
	s_nop 1
	v_permlane32_swap_b32 v246, v245
	v_add_f32_e32 v245, v246, v245
	v_mov_b32_e32 v246, 0x3c000000
	v_fmaak_f32 v245, v245, v246, 0x358637bd
	v_rsq_f32_e32 v245, v245
	s_nop 0
	v_mul_f32_e32 v245, 0x3f4ccccd, v245
	s_lshl_b32 s6, s11, 11
	s_add_i32 s6, s6, s15
	s_lshl_b32 s6, s6, 11
	s_lshl_b32 s7, s81, 1
	s_add_i32 s6, s6, s7
	s_add_u32 s20, s70, s6
	s_addc_u32 s21, s71, 0
	v_and_b32_e32 v242, 31, v219
	v_lshlrev_b32_e32 v242, 11, v242
	v_lshrrev_b32_e32 v243, 5, v219
	v_lshl_add_u32 v242, v243, 3, v242
	s_waitcnt vmcnt(0)
; __device__ __forceinline__ unsigned pk_bf16(float lo, float hi) { f32x2 v = {lo, hi}; bf16x2_t b = __builtin_convertvector(v, bf16x2_t); return __builtin_bit_cast(unsigned, b); }
; __device__ __forceinline__ void subln_store(f32x16 (&o)[4], const float* subg, bf16_t* dst  , int lane) {
;     ...
;     for (int cb = 0; cb < 4; ++cb)
; #pragma unroll
;         for (int g = 0; g < 4; ++g) { const int dv0 = 32 * cb + 8 * g + 4 * hi; const f32x4 s4 = sg[cb][g];
;             u32x2 w; w.x = pk_bf16(o[cb][4 * g + 0] * rstd * s4[0], o[cb][4 * g + 1] * rstd * s4[1]); w.y = pk_bf16(o[cb][4 * g + 2] * rstd * s4[2], o[cb][4 * g + 3] * rstd * s4[3]);
;             *(u32x2*)(dst + dv0) = w; }
	v_mul_f32_e32 v4, v4, v245
	v_mul_f32_e32 v5, v5, v245
	v_mul_f32_e32 v6, v6, v245
	v_mul_f32_e32 v7, v7, v245
	v_mul_f32_e32 v4, v4, v100
	v_mul_f32_e32 v5, v5, v101
	v_mul_f32_e32 v6, v6, v102
	v_mul_f32_e32 v7, v7, v103
	v_cvt_pk_bf16_f32 v68, v4, v5
	v_cvt_pk_bf16_f32 v69, v6, v7
	global_store_dwordx2 v242, v[68:69], s[20:21] offset:0
	v_mul_f32_e32 v8, v8, v245
	v_mul_f32_e32 v9, v9, v245
	v_mul_f32_e32 v10, v10, v245
	v_mul_f32_e32 v11, v11, v245
	v_mul_f32_e32 v8, v8, v104
	v_mul_f32_e32 v9, v9, v105
	v_mul_f32_e32 v10, v10, v106
	v_mul_f32_e32 v11, v11, v107
	v_cvt_pk_bf16_f32 v70, v8, v9
	v_cvt_pk_bf16_f32 v71, v10, v11
	global_store_dwordx2 v242, v[70:71], s[20:21] offset:16
	v_mul_f32_e32 v12, v12, v245
	v_mul_f32_e32 v13, v13, v245
	v_mul_f32_e32 v14, v14, v245
	v_mul_f32_e32 v15, v15, v245
	v_mul_f32_e32 v12, v12, v108
	v_mul_f32_e32 v13, v13, v109
	v_mul_f32_e32 v14, v14, v110
	v_mul_f32_e32 v15, v15, v111
	v_cvt_pk_bf16_f32 v68, v12, v13
	v_cvt_pk_bf16_f32 v69, v14, v15
	global_store_dwordx2 v242, v[68:69], s[20:21] offset:32
	v_mul_f32_e32 v16, v16, v245
	v_mul_f32_e32 v17, v17, v245
	v_mul_f32_e32 v18, v18, v245
	v_mul_f32_e32 v19, v19, v245
	v_mul_f32_e32 v16, v16, v112
	v_mul_f32_e32 v17, v17, v113
	v_mul_f32_e32 v18, v18, v114
	v_mul_f32_e32 v19, v19, v115
	v_cvt_pk_bf16_f32 v70, v16, v17
	v_cvt_pk_bf16_f32 v71, v18, v19
	global_store_dwordx2 v242, v[70:71], s[20:21] offset:48
	v_mul_f32_e32 v20, v20, v245
	v_mul_f32_e32 v21, v21, v245
	v_mul_f32_e32 v22, v22, v245
	v_mul_f32_e32 v23, v23, v245
	v_mul_f32_e32 v20, v20, v116
	v_mul_f32_e32 v21, v21, v117
	v_mul_f32_e32 v22, v22, v118
	v_mul_f32_e32 v23, v23, v119
	v_cvt_pk_bf16_f32 v68, v20, v21
	v_cvt_pk_bf16_f32 v69, v22, v23
	global_store_dwordx2 v242, v[68:69], s[20:21] offset:64
	v_mul_f32_e32 v24, v24, v245
	v_mul_f32_e32 v25, v25, v245
	v_mul_f32_e32 v26, v26, v245
	v_mul_f32_e32 v27, v27, v245
	v_mul_f32_e32 v24, v24, v120
	v_mul_f32_e32 v25, v25, v121
	v_mul_f32_e32 v26, v26, v122
	v_mul_f32_e32 v27, v27, v123
	v_cvt_pk_bf16_f32 v70, v24, v25
	v_cvt_pk_bf16_f32 v71, v26, v27
	global_store_dwordx2 v242, v[70:71], s[20:21] offset:80
	v_mul_f32_e32 v28, v28, v245
	v_mul_f32_e32 v29, v29, v245
	v_mul_f32_e32 v30, v30, v245
	v_mul_f32_e32 v31, v31, v245
	v_mul_f32_e32 v28, v28, v124
	v_mul_f32_e32 v29, v29, v125
	v_mul_f32_e32 v30, v30, v126
	v_mul_f32_e32 v31, v31, v127
	v_cvt_pk_bf16_f32 v68, v28, v29
	v_cvt_pk_bf16_f32 v69, v30, v31
	global_store_dwordx2 v242, v[68:69], s[20:21] offset:96
	v_mul_f32_e32 v32, v32, v245
	v_mul_f32_e32 v33, v33, v245
	v_mul_f32_e32 v34, v34, v245
	v_mul_f32_e32 v35, v35, v245
	v_mul_f32_e32 v32, v32, v128
	v_mul_f32_e32 v33, v33, v129
	v_mul_f32_e32 v34, v34, v130
	v_mul_f32_e32 v35, v35, v131
	v_cvt_pk_bf16_f32 v70, v32, v33
	v_cvt_pk_bf16_f32 v71, v34, v35
	global_store_dwordx2 v242, v[70:71], s[20:21] offset:112
	v_mul_f32_e32 v36, v36, v245
	v_mul_f32_e32 v37, v37, v245
	v_mul_f32_e32 v38, v38, v245
	v_mul_f32_e32 v39, v39, v245
	v_mul_f32_e32 v36, v36, v132
	v_mul_f32_e32 v37, v37, v133
	v_mul_f32_e32 v38, v38, v134
	v_mul_f32_e32 v39, v39, v135
	v_cvt_pk_bf16_f32 v68, v36, v37
	v_cvt_pk_bf16_f32 v69, v38, v39
	global_store_dwordx2 v242, v[68:69], s[20:21] offset:128
	v_mul_f32_e32 v40, v40, v245
	v_mul_f32_e32 v41, v41, v245
	v_mul_f32_e32 v42, v42, v245
	v_mul_f32_e32 v43, v43, v245
	v_mul_f32_e32 v40, v40, v136
	v_mul_f32_e32 v41, v41, v137
	v_mul_f32_e32 v42, v42, v138
	v_mul_f32_e32 v43, v43, v139
	v_cvt_pk_bf16_f32 v70, v40, v41
	v_cvt_pk_bf16_f32 v71, v42, v43
	global_store_dwordx2 v242, v[70:71], s[20:21] offset:144
	v_mul_f32_e32 v44, v44, v245
	v_mul_f32_e32 v45, v45, v245
	v_mul_f32_e32 v46, v46, v245
	v_mul_f32_e32 v47, v47, v245
	v_mul_f32_e32 v44, v44, v140
	v_mul_f32_e32 v45, v45, v141
	v_mul_f32_e32 v46, v46, v142
	v_mul_f32_e32 v47, v47, v143
	v_cvt_pk_bf16_f32 v68, v44, v45
	v_cvt_pk_bf16_f32 v69, v46, v47
	global_store_dwordx2 v242, v[68:69], s[20:21] offset:160
	v_mul_f32_e32 v48, v48, v245
	v_mul_f32_e32 v49, v49, v245
	v_mul_f32_e32 v50, v50, v245
	v_mul_f32_e32 v51, v51, v245
	v_mul_f32_e32 v48, v48, v144
	v_mul_f32_e32 v49, v49, v145
	v_mul_f32_e32 v50, v50, v146
	v_mul_f32_e32 v51, v51, v147
	v_cvt_pk_bf16_f32 v70, v48, v49
	v_cvt_pk_bf16_f32 v71, v50, v51
	global_store_dwordx2 v242, v[70:71], s[20:21] offset:176
	v_mul_f32_e32 v52, v52, v245
	v_mul_f32_e32 v53, v53, v245
	v_mul_f32_e32 v54, v54, v245
	v_mul_f32_e32 v55, v55, v245
	v_mul_f32_e32 v52, v52, v148
	v_mul_f32_e32 v53, v53, v149
	v_mul_f32_e32 v54, v54, v150
	v_mul_f32_e32 v55, v55, v151
	v_cvt_pk_bf16_f32 v68, v52, v53
	v_cvt_pk_bf16_f32 v69, v54, v55
	global_store_dwordx2 v242, v[68:69], s[20:21] offset:192
	v_mul_f32_e32 v56, v56, v245
	v_mul_f32_e32 v57, v57, v245
	v_mul_f32_e32 v58, v58, v245
	v_mul_f32_e32 v59, v59, v245
	v_mul_f32_e32 v56, v56, v152
	v_mul_f32_e32 v57, v57, v153
	v_mul_f32_e32 v58, v58, v154
	v_mul_f32_e32 v59, v59, v155
	v_cvt_pk_bf16_f32 v70, v56, v57
	v_cvt_pk_bf16_f32 v71, v58, v59
	global_store_dwordx2 v242, v[70:71], s[20:21] offset:208
	v_mul_f32_e32 v60, v60, v245
	v_mul_f32_e32 v61, v61, v245
	v_mul_f32_e32 v62, v62, v245
	v_mul_f32_e32 v63, v63, v245
	v_mul_f32_e32 v60, v60, v156
	v_mul_f32_e32 v61, v61, v157
	v_mul_f32_e32 v62, v62, v158
	v_mul_f32_e32 v63, v63, v159
	v_cvt_pk_bf16_f32 v68, v60, v61
	v_cvt_pk_bf16_f32 v69, v62, v63
	global_store_dwordx2 v242, v[68:69], s[20:21] offset:224
	v_mul_f32_e32 v64, v64, v245
	v_mul_f32_e32 v65, v65, v245
	v_mul_f32_e32 v66, v66, v245
	v_mul_f32_e32 v67, v67, v245
	v_mul_f32_e32 v64, v64, v160
	v_mul_f32_e32 v65, v65, v161
	v_mul_f32_e32 v66, v66, v162
	v_mul_f32_e32 v67, v67, v163
	v_cvt_pk_bf16_f32 v70, v64, v65
	v_cvt_pk_bf16_f32 v71, v66, v67
	global_store_dwordx2 v242, v[70:71], s[20:21] offset:240
